# fast device-memory grid barrier; attention hot loop VALU trim (max3+permlane32_swap, counted lgkm waits); XCD-aware unit remap for attention and HGRN2 recurrence; pipelined final norm
# speedup vs baseline: 1.0475x; 1.0370x over previous
; #define LAS __attribute__((address_space(3)))
; __device__ __forceinline__ void hg_recur(LAS unsigned char* lds, const bf16_t* QF, bf16_t* IG, const bf16_t* P, const float* Dg, float* ssq_o, int G, int bid) {
;     int tid_l = threadIdx.x; asm volatile("" : "+v"(tid_l));
;     const int tid = tid_l, w = tid >> 6, lane = tid & 63, lv = lane & 15, fq = lane >> 4, vt = w & 1, kq = w >> 1;
;     const int srow = tid >> 4, sch = tid & 15;
;     for (int u = bid; u < 256; u += G) {
;         const int b = u >> 5, h = (u >> 2) & 7, vq = u & 3;
;         f32x4 S[2];
;         S[0] = (f32x4){0.f, 0.f, 0.f, 0.f}; S[1] = S[0];
.LBB0_392:
	s_or_b64 exec, exec, s[8:9]
	s_mov_b64 s[8:9], s[0:1]
	s_mov_b64 s[10:11], s[0:1]
	s_mov_b64 s[12:13], s[0:1]
	s_mov_b64 s[14:15], s[0:1]
	s_mov_b64 s[16:17], s[0:1]
	v_mov_b32_e32 v0, v218
	s_cmpk_gt_i32 s2, 0xff
	s_movk_i32 s3, 0xff
	s_barrier
	s_cbranch_scc1 .LBB0_554
	s_load_dwordx2 s[4:5], s[8:9], 0xc8
	s_load_dwordx2 s[46:47], s[10:11], 0xc8
	s_load_dwordx2 s[6:7], s[12:13], 0xc8
	s_load_dwordx2 s[18:19], s[14:15], 0xc8
	s_load_dwordx2 s[48:49], s[16:17], 0xc8
	s_waitcnt lgkmcnt(0)
	s_add_u32 s20, s4, 0x1c000000
	s_addc_u32 s21, s5, 0
	s_add_u32 s22, s46, 0xc000000
	s_addc_u32 s23, s47, 0
	s_add_u32 s24, s6, 0x4000000
	s_addc_u32 s25, s7, 0
	s_add_u32 s26, s18, 0x6000000
	v_cmp_lt_u32_e64 s[10:11], s3, v0
	s_movk_i32 s3, 0x120
	s_addc_u32 s27, s19, 0
	v_cmp_gt_u32_e64 s[12:13], s3, v0
	v_mov_b32_e32 v4, 0xfffffc00
	s_movk_i32 s3, 0x80
	s_add_u32 s40, s48, 0x3c00000
	v_ashrrev_i32_e32 v40, 4, v0
	v_ashrrev_i32_e32 v3, 7, v0
	v_lshl_add_u32 v44, v0, 2, v4
	v_subrev_co_u32_e32 v4, vcc, s3, v0
	s_movk_i32 s3, 0x110
	s_addc_u32 s41, s49, 0
	s_movk_i32 s4, 0x7f
	s_xor_b64 s[42:43], vcc, -1
	v_mul_lo_u32 v6, v40, s3
	v_cmp_lt_i32_e32 vcc, 0, v3
	v_and_b32_e32 v1, 15, v0
	v_mov_b32_e32 v43, 0
	v_cmp_lt_i32_e64 s[8:9], s4, v0
	v_add_u32_e32 v85, 0, v6
	v_bfe_u32 v6, v0, 2, 2
	s_movk_i32 s4, 0xff70
	v_cndmask_b32_e64 v17, 0, 16, vcc
	v_lshlrev_b32_e32 v2, 3, v1
	v_lshlrev_b32_e32 v48, 4, v1
	v_lshl_or_b32 v6, v40, 2, v6
	s_movk_i32 s3, 0x50
	v_mov_b32_e32 v49, v43
	v_mul_lo_u32 v14, v40, s4
	v_or_b32_e32 v17, v17, v1
	v_cmp_eq_u32_e32 vcc, 2, v3
	v_mul_lo_u32 v6, v6, s3
	v_lshl_add_u64 v[50:51], s[20:21], 0, v[48:49]
	v_lshlrev_b32_e32 v13, 7, v40
	v_add3_u32 v49, v85, v14, v2
	v_mul_u32_u24_e32 v14, 0x110, v1
	v_lshlrev_b32_e32 v15, 6, v3
	v_mul_u32_u24_e32 v17, 0x50, v17
	v_cndmask_b32_e64 v18, 0, 32, vcc
	v_lshlrev_b32_e32 v19, 5, v3
	s_add_i32 s4, 0, 0x10000
	v_bfe_u32 v5, v0, 6, 1
	v_bfe_u32 v7, v0, 4, 2
	v_lshlrev_b32_e32 v46, 3, v0
	s_waitcnt vmcnt(0)
	v_add_u32_e32 v8, 0, v6
	v_lshlrev_b32_e32 v86, 4, v0
	v_lshrrev_b32_e32 v6, 2, v0
	v_add3_u32 v93, s4, v13, v2
	v_add3_u32 v13, 0, v14, v15
	v_add3_u32 v14, 0, v17, v18
	v_and_b32_e32 v17, 0xffffff80, v0
	v_or_b32_e32 v0, v19, v1
	v_lshlrev_b32_e32 v12, 5, v5
	v_cmp_gt_i32_e64 s[16:17], 3, v3
	v_cmp_ne_u32_e64 s[18:19], 1, v3
	v_lshlrev_b32_e32 v3, 12, v3
	v_lshlrev_b32_e32 v5, 6, v5
	v_mul_lo_u32 v18, v0, s3
	v_or_b32_e32 v0, 16, v19
	v_ashrrev_i32_e32 v41, 31, v40
	v_add3_u32 v3, 0, v3, v5
	v_lshlrev_b32_e32 v5, 2, v1
	v_lshlrev_b32_e32 v20, 9, v7
	v_lshlrev_b32_e32 v19, 2, v0
	v_or_b32_e32 v0, v0, v1
	v_mul_lo_u32 v88, v6, s3
	v_lshlrev_b32_e32 v6, 1, v1
	v_cmp_eq_u32_e64 s[14:15], 0, v1
	v_add3_u32 v91, v3, v5, v20
	v_mul_lo_u32 v20, v0, s3
	v_lshlrev_b64 v[0:1], 5, v[40:41]
	v_lshl_add_u64 v[0:1], s[48:49], 0, v[0:1]
	s_mov_b64 s[4:5], 0x3c00800
	v_lshrrev_b32_e32 v84, 2, v4
	v_lshl_add_u64 v[56:57], v[0:1], 0, s[4:5]
	v_lshlrev_b64 v[0:1], 12, v[40:41]
	v_mul_lo_u32 v87, v84, s3
	v_lshlrev_b32_e32 v16, 3, v7
	v_add3_u32 v3, 0, v12, v6
	v_mul_u32_u24_e32 v12, 0x140, v7
	v_lshl_add_u32 v7, v7, 4, 0
	v_or_b32_e32 v0, v0, v5
	v_mov_b32_e32 v45, v43
	v_and_b32_e32 v4, 24, v46
	v_ashrrev_i32_e32 v47, 31, v46
	v_and_b32_e32 v9, 48, v86
	v_add_u32_e32 v10, 0, v87
	v_add_u32_e32 v11, 0, v88
	v_sub_u32_e32 v15, v7, v16
	v_lshl_add_u64 v[0:1], s[46:47], 0, v[0:1]
	s_mov_b64 s[4:5], 0xc040000
	s_mov_b32 s45, 0
	v_add_u32_e32 v89, 0, v9
	v_lshl_add_u64 v[52:53], v[44:45], 2, s[26:27]
	v_lshl_add_u64 v[54:55], v[46:47], 1, s[24:25]
	v_add_u32_e32 v90, 0xc000, v49
	v_add_u32_e32 v92, 0xc000, v91
	v_add_u32_e32 v94, 0xa0, v40
	v_lshl_add_u64 v[58:59], v[0:1], 0, s[4:5]
	v_lshlrev_b32_e32 v42, 1, v2
	v_add_u32_e32 v95, v10, v9
	v_add_u32_e32 v96, v11, v9
	v_lshlrev_b32_e32 v60, 1, v4
	s_mov_b32 s3, 0xfffe0000
	s_mov_b64 s[46:47], 0x800
	s_mov_b64 s[48:49], 0x40000
	v_lshlrev_b32_e32 v62, 1, v6
	v_add_u32_e32 v97, v8, v9
	v_add_u32_e32 v98, v3, v12
	v_add_u32_e32 v99, v13, v16
	v_add_u32_e32 v100, v14, v16
	v_add_u32_e32 v101, v7, v17
	v_add_u32_e32 v102, v15, v18
	v_add_u32_e32 v103, v7, v19
	v_add_u32_e32 v104, v15, v20
	s_mov_b32 s4, s2
	s_mov_b32 s5, s70
	s_mov_b32 s6, s2
	s_cmp_lg_u32 s34, 0x100
	s_cbranch_scc1 .Lrec_noremap
	s_and_b32 s4, s2, 7
	s_lshl_b32 s4, s4, 5
	s_lshr_b32 s6, s2, 3
	s_add_i32 s4, s4, s6
	s_mov_b32 s6, s4
	s_lshl_b32 s5, s4, 3
.Lrec_noremap:
	s_branch .LBB0_395
.LBB0_394:
	s_or_b64 exec, exec, s[50:51]
	s_waitcnt lgkmcnt(0)
	s_barrier
	s_add_i32 s6, s6, s34
	s_add_i32 s5, s5, s28
	s_add_i32 s4, s4, s34
	s_cmpk_lt_i32 s6, 0x100
	s_cbranch_scc0 .LBB0_554

; #define LAS __attribute__((address_space(3)))
; template <int MODE> __device__ __forceinline__ void attn_phase(LAS unsigned char* lds, const bf16_t* Q, const bf16_t* KF, const bf16_t* VT, bf16_t* O, const int* positions, const float* gq, int G, int bid) {
;     int tid_l = threadIdx.x; asm volatile("" : "+v"(tid_l));
;     const int tid = tid_l, w = tid >> 6, lane = tid & 63, lq = lane & 31, hi = lane >> 5;
;     const unsigned kvo = (unsigned)((tid >> 3) * 1536 + 8 * (tid & 7));
;     const unsigned vvo = (unsigned)((tid >> 3) * T + 8 * (tid & 7));
;     const unsigned klo = (unsigned)((tid >> 3) * AT_KP + (tid & 7) * 16);
;     const unsigned vlo = (unsigned)(AT_KBYTES + (tid >> 3) * AT_VP + ((tid & 7) >> 1) * 32 + (tid & 1) * 8);
;     for (int it = bid; it < 1024; it += G) {
;     ...
;                     for (int j = 0; j < 8; ++j) {
;                         const int i = 16 * (kk - 8) + 8 * hi + j;
;                         const float ang = pos * exp2f(-(float)i * 0.41524101186092029f);
;                         const double rev = (double)ang * 0.15915494309189535; const float frc = (float)(rev - rint(rev));
;                         const float sn = __builtin_amdgcn_sinf(frc), cs = __builtin_amdgcn_cosf(frc);
.LBB0_661:
	s_or_b64 exec, exec, s[8:9]
	s_mov_b64 s[8:9], s[0:1]
	s_mov_b64 s[12:13], s[0:1]
	s_mov_b64 s[10:11], s[0:1]
	s_mov_b64 s[14:15], s[0:1]
	s_mov_b64 s[18:19], s[0:1]
	s_mov_b64 s[16:17], s[0:1]
	v_mov_b32_e32 v0, v218
	s_and_b64 vcc, exec, s[74:75]
	s_barrier
	s_cbranch_vccnz .LBB0_683
	v_lshlrev_b32_e32 v3, 4, v0
	s_load_dwordx2 s[4:5], s[12:13], 0xc8
	s_load_dwordx2 s[6:7], s[8:9], 0xc8
	s_load_dwordx2 s[22:23], s[10:11], 0xc8
	s_load_dwordx2 s[24:25], s[14:15], 0xc8
	s_load_dwordx2 s[20:21], s[18:19], 0x8
	v_ashrrev_i32_e32 v1, 3, v0
	v_and_b32_e32 v2, 0x70, v3
	s_movk_i32 s8, 0x190
	v_mad_u64_u32 v[200:201], s[8:9], v1, s8, v[2:3]
	v_lshlrev_b32_e32 v9, 3, v0
	v_and_b32_e32 v10, 31, v0
	v_bfe_u32 v11, v0, 5, 1
	v_ashrrev_i32_e32 v201, 7, v0
	v_ashrrev_i32_e32 v0, 1, v0
	v_and_b32_e32 v0, 0xffffffe0, v0
	v_ashrrev_i32_e32 v203, 31, v0
	v_or_b32_e32 v202, v0, v10
	v_mov_b32_e32 v0, 0
	v_lshlrev_b32_e32 v204, 4, v11
	v_mov_b32_e32 v205, v0
	s_waitcnt lgkmcnt(0)
	v_lshl_add_u64 v[6:7], s[6:7], 0, v[204:205]
	s_mov_b64 s[6:7], 0x1c000000
	s_add_u32 s3, s4, 0x31800000
	v_lshl_add_u64 v[206:207], v[6:7], 0, s[6:7]
	v_mbcnt_hi_u32_b32 v6, -1, v219
	s_addc_u32 s29, s5, 0
	s_load_dwordx2 s[4:5], s[16:17], 0x70
	v_and_b32_e32 v12, 64, v6
	v_xor_b32_e32 v7, 32, v6
	v_add_u32_e32 v12, 64, v12
	v_cmp_lt_i32_e32 vcc, v7, v12
	s_movk_i32 s8, 0x90
	v_mul_lo_u32 v8, v1, s8
	v_cndmask_b32_e32 v6, v6, v7, vcc
	v_lshlrev_b32_e32 v205, 2, v6
	v_lshlrev_b32_e32 v6, 5, v11
	v_mov_b32_e32 v7, v0
	s_movk_i32 s37, 0xc00
	v_and_b32_e32 v3, 0x60, v3
	v_lshlrev_b32_e32 v4, 3, v11
	v_mov_b32_e32 v5, v0
	s_waitcnt lgkmcnt(0)
	v_lshl_add_u64 v[208:209], s[4:5], 0, v[6:7]
	v_mul_lo_u32 v6, v1, s37
	v_lshl_or_b32 v221, v1, 17, v2
	v_and_or_b32 v1, v9, 8, v8
	v_or_b32_e32 v220, v2, v6
	v_add_u32_e32 v222, v1, v3
	v_lshl_add_u64 v[2:3], s[24:25], 0, v[4:5]
	s_mov_b64 s[4:5], 0xc000000
	v_cvt_f32_ubyte0_e32 v1, v4
	v_or_b32_e32 v5, 1, v4
	v_lshl_add_u64 v[210:211], v[2:3], 0, s[4:5]
	v_mul_f32_e32 v2, 0xbed49a78, v1
	s_mov_b32 s4, 0xc2fc0000
	v_cvt_f32_ubyte0_e32 v5, v5
	v_mov_b32_e32 v3, 0x42800000
	v_cmp_gt_f32_e32 vcc, s4, v2
	v_mul_f32_e32 v6, 0xbed49a78, v5
	v_cmp_gt_f32_e64 s[8:9], s4, v6
	v_cndmask_b32_e32 v2, 0, v3, vcc
	v_fmac_f32_e32 v2, 0xbed49a78, v1
	v_cndmask_b32_e64 v6, 0, v3, s[8:9]
	v_exp_f32_e32 v1, v2
	v_fmac_f32_e32 v6, 0xbed49a78, v5
	v_exp_f32_e32 v5, v6
	v_not_b32_e32 v2, 63
	v_cndmask_b32_e32 v6, 0, v2, vcc
	v_ldexp_f32 v224, v1, v6
	v_cndmask_b32_e64 v1, 0, v2, s[8:9]
	v_ldexp_f32 v225, v5, v1
	v_or_b32_e32 v1, 2, v4
	v_cvt_f32_ubyte0_e32 v1, v1
	v_mul_f32_e32 v5, 0xbed49a78, v1
	v_cmp_gt_f32_e32 vcc, s4, v5
	s_add_u32 s33, s22, 0x4000000
	s_mov_b32 s24, 0x6dc9c883
	v_cndmask_b32_e32 v5, 0, v3, vcc
	v_fmac_f32_e32 v5, 0xbed49a78, v1
	v_exp_f32_e32 v1, v5
	v_or_b32_e32 v5, 3, v4
	v_cvt_f32_ubyte0_e32 v5, v5
	v_mul_f32_e32 v6, 0xbed49a78, v5
	v_cmp_gt_f32_e64 s[8:9], s4, v6
	s_addc_u32 s35, s23, 0
	s_mov_b32 s23, 0
	v_cndmask_b32_e64 v6, 0, v3, s[8:9]
	v_fmac_f32_e32 v6, 0xbed49a78, v5
	v_exp_f32_e32 v5, v6
	v_cndmask_b32_e32 v6, 0, v2, vcc
	v_ldexp_f32 v226, v1, v6
	v_cndmask_b32_e64 v1, 0, v2, s[8:9]
	v_ldexp_f32 v227, v5, v1
	v_or_b32_e32 v1, 4, v4
	v_cvt_f32_ubyte0_e32 v1, v1
	v_mul_f32_e32 v5, 0xbed49a78, v1
	v_cmp_gt_f32_e32 vcc, s4, v5
	v_mul_u32_u24_e32 v223, 0x190, v10
	v_or_b32_e32 v240, 0x80, v220
	v_cndmask_b32_e32 v5, 0, v3, vcc
	v_fmac_f32_e32 v5, 0xbed49a78, v1
	v_exp_f32_e32 v1, v5
	v_or_b32_e32 v5, 5, v4
	v_cvt_f32_ubyte0_e32 v5, v5
	v_mul_f32_e32 v6, 0xbed49a78, v5
	v_cmp_gt_f32_e64 s[8:9], s4, v6
	v_or_b32_e32 v241, 0x100, v220
	v_mul_u32_u24_e32 v242, 0x90, v10
	v_cndmask_b32_e64 v6, 0, v3, s[8:9]
	v_fmac_f32_e32 v6, 0xbed49a78, v5
	v_exp_f32_e32 v5, v6
	v_cndmask_b32_e32 v6, 0, v2, vcc
	v_ldexp_f32 v228, v1, v6
	v_cndmask_b32_e64 v1, 0, v2, s[8:9]
	v_ldexp_f32 v229, v5, v1
	v_or_b32_e32 v1, 6, v4
	v_cvt_f32_ubyte0_e32 v1, v1
	v_mul_f32_e32 v5, 0xbed49a78, v1
	v_cmp_gt_f32_e32 vcc, s4, v5
	s_mov_b32 s15, 0x20000
	s_brev_b32 s14, -2
	v_cndmask_b32_e32 v5, 0, v3, vcc
	v_fmac_f32_e32 v5, 0xbed49a78, v1
	v_exp_f32_e32 v1, v5
	v_or_b32_e32 v5, 7, v4
	v_cvt_f32_ubyte0_e32 v5, v5
	v_mul_f32_e32 v6, 0xbed49a78, v5
	v_cmp_gt_f32_e64 s[8:9], s4, v6
	v_mov_b32_e32 v243, 0x358637bd
	s_mov_b32 s46, 0x800000
	v_cndmask_b32_e64 v6, 0, v3, s[8:9]
	v_fmac_f32_e32 v6, 0xbed49a78, v5
	v_exp_f32_e32 v5, v6
	v_cndmask_b32_e32 v6, 0, v2, vcc
	v_ldexp_f32 v230, v1, v6
	v_cndmask_b32_e64 v1, 0, v2, s[8:9]
	v_ldexp_f32 v231, v5, v1
	v_or_b32_e32 v1, 16, v4
	v_cvt_f32_ubyte0_e32 v1, v1
	v_mul_f32_e32 v5, 0xbed49a78, v1
	v_cmp_gt_f32_e32 vcc, s4, v5
	s_mov_b32 s25, 0x3fc45f30
	s_mov_b32 s47, 0x40c00000
	v_cndmask_b32_e32 v5, 0, v3, vcc
	v_fmac_f32_e32 v5, 0xbed49a78, v1
	v_exp_f32_e32 v1, v5
	v_or_b32_e32 v5, 17, v4
	v_cvt_f32_ubyte0_e32 v5, v5
	v_mul_f32_e32 v6, 0xbed49a78, v5
	v_cmp_gt_f32_e64 s[8:9], s4, v6
	s_mov_b32 s48, s2
	s_cmp_lg_u32 s34, 0x100
	s_cbranch_scc1 .Lattn_noremap
	s_and_b32 s48, s2, 7
	s_lshl_b32 s48, s48, 5
	s_lshr_b32 s49, s2, 3
	s_add_i32 s48, s48, s49
.Lattn_noremap:
	s_nop 0
	v_cndmask_b32_e64 v6, 0, v3, s[8:9]
	v_fmac_f32_e32 v6, 0xbed49a78, v5
	v_exp_f32_e32 v5, v6
	v_cndmask_b32_e32 v6, 0, v2, vcc
	v_ldexp_f32 v232, v1, v6
	v_cndmask_b32_e64 v1, 0, v2, s[8:9]
	v_ldexp_f32 v233, v5, v1
	v_or_b32_e32 v1, 18, v4
	v_cvt_f32_ubyte0_e32 v1, v1
	v_mul_f32_e32 v5, 0xbed49a78, v1
	v_cmp_gt_f32_e32 vcc, s4, v5
	s_nop 1
	v_cndmask_b32_e32 v5, 0, v3, vcc
	v_fmac_f32_e32 v5, 0xbed49a78, v1
	v_exp_f32_e32 v1, v5
	v_or_b32_e32 v5, 19, v4
	v_cvt_f32_ubyte0_e32 v5, v5
	v_mul_f32_e32 v6, 0xbed49a78, v5
	v_cmp_gt_f32_e64 s[8:9], s4, v6
	s_nop 1
	v_cndmask_b32_e64 v6, 0, v3, s[8:9]
	v_fmac_f32_e32 v6, 0xbed49a78, v5
	v_exp_f32_e32 v5, v6
	v_cndmask_b32_e32 v6, 0, v2, vcc
	v_ldexp_f32 v234, v1, v6
	v_cndmask_b32_e64 v1, 0, v2, s[8:9]
	v_ldexp_f32 v235, v5, v1
	v_or_b32_e32 v1, 20, v4
	v_cvt_f32_ubyte0_e32 v1, v1
	v_mul_f32_e32 v5, 0xbed49a78, v1
	v_cmp_gt_f32_e32 vcc, s4, v5
	s_nop 1
	v_cndmask_b32_e32 v5, 0, v3, vcc
	v_fmac_f32_e32 v5, 0xbed49a78, v1
	v_exp_f32_e32 v1, v5
	v_or_b32_e32 v5, 21, v4
	v_cvt_f32_ubyte0_e32 v5, v5
	v_mul_f32_e32 v6, 0xbed49a78, v5
	v_cmp_gt_f32_e64 s[8:9], s4, v6
	s_nop 1
	v_cndmask_b32_e64 v6, 0, v3, s[8:9]
	v_fmac_f32_e32 v6, 0xbed49a78, v5
	v_exp_f32_e32 v5, v6
	v_cndmask_b32_e32 v6, 0, v2, vcc
	v_ldexp_f32 v236, v1, v6
	v_cndmask_b32_e64 v1, 0, v2, s[8:9]
	v_ldexp_f32 v237, v5, v1
	v_or_b32_e32 v1, 22, v4
	v_cvt_f32_ubyte0_e32 v1, v1
	v_mul_f32_e32 v5, 0xbed49a78, v1
	v_cmp_gt_f32_e32 vcc, s4, v5
	v_or_b32_e32 v4, 23, v4
	v_cvt_f32_ubyte0_e32 v4, v4
	v_cndmask_b32_e32 v5, 0, v3, vcc
	v_fmac_f32_e32 v5, 0xbed49a78, v1
	v_exp_f32_e32 v1, v5
	v_mul_f32_e32 v5, 0xbed49a78, v4
	v_cmp_gt_f32_e64 s[8:9], s4, v5
	s_nop 1
	v_cndmask_b32_e64 v3, 0, v3, s[8:9]
	v_fmac_f32_e32 v3, 0xbed49a78, v4
	v_exp_f32_e32 v3, v3
	v_cndmask_b32_e32 v4, 0, v2, vcc
	v_ldexp_f32 v238, v1, v4
	v_cndmask_b32_e64 v1, 0, v2, s[8:9]
	v_ldexp_f32 v239, v3, v1
	v_cmp_lt_i32_e64 s[8:9], 2, v201
	s_branch .LBB0_664

; #define LAS __attribute__((address_space(3)))
; template <int MODE> __device__ __forceinline__ void attn_phase(LAS unsigned char* lds, const bf16_t* Q, const bf16_t* KF, const bf16_t* VT, bf16_t* O, const int* positions, const float* gq, int G, int bid) {
;     ...
;             for (int kt = 0; kt < ntiles; ++kt) {
;                 const bool more = (kt + 1 < ntiles);
;                 if (more && MODE < 3) { AT_GLOAD_K(kt + 1); AT_GLOAD_V(kt + 1); }
;                 if (kt <= my_last) {
;                     LAS unsigned char* kb = lds + (kt & 1) * AT_STAGE; LAS unsigned char* vb = kb + AT_KBYTES;
;     ...
;                     f32x16 s0, s1;
; #pragma unroll
;                     for (int i = 0; i < 16; ++i) s0[i] = -mrun;
;                     bf16x8 fr[8], fr2[4];
; #pragma unroll
;                     for (int kk = 0; kk < 8; ++kk) fr[kk] = *(const LAS bf16x8*)(kb + lq * AT_KP + (16 * kk + 8 * hi) * 2);
;                     __builtin_amdgcn_sched_barrier(0);
; #pragma unroll
;                     for (int kk = 0; kk < 4; ++kk) s0 = __builtin_amdgcn_mfma_f32_32x32x16_bf16(fr[kk], qf[kk], s0, 0, 0, 0);
;                     __builtin_amdgcn_sched_barrier(0);
; #pragma unroll
;                     for (int kk = 8; kk < 12; ++kk) fr2[kk - 8] = *(const LAS bf16x8*)(kb + lq * AT_KP + (16 * kk + 8 * hi) * 2);
;                     __builtin_amdgcn_sched_barrier(0);
; #pragma unroll
;                     for (int kk = 4; kk < 8; ++kk) s0 = __builtin_amdgcn_mfma_f32_32x32x16_bf16(fr[kk], qf[kk], s0, 0, 0, 0);
; #pragma unroll
;                     for (int kk = 8; kk < 12; ++kk) s0 = __builtin_amdgcn_mfma_f32_32x32x16_bf16(fr2[kk - 8], qf[kk], s0, 0, 0, 0);
;                     __builtin_amdgcn_sched_barrier(0);
; #pragma unroll
;                     for (int kk = 0; kk < 8; ++kk) fr[kk] = *(const LAS bf16x8*)(kb + (32 + lq) * AT_KP + (16 * kk + 8 * hi) * 2);
;                     __builtin_amdgcn_sched_barrier(0);
;                     float mx = fmaxf(fmaxf(s0[0], s0[1]), fmaxf(s0[2], s0[3]));
; #pragma unroll
;                     for (int i = 4; i < 16; i += 2) mx = fmaxf(mx, fmaxf(s0[i], s0[i + 1]));
;                     mx = fmaxf(mx, __shfl_xor(mx, 32));
;                     if (__any(mx > 6.0f)) AT_RESCALE(_Pragma("unroll") for (int i = 0; i < 16; ++i) s0[i] -= d_;);
.LBB0_668:
	buffer_load_dwordx4 v[10:13], v220, s[12:15], s6 offen
	buffer_load_dwordx4 v[160:163], v240, s[12:15], s6 offen
	buffer_load_dwordx4 v[164:167], v241, s[12:15], s6 offen
	s_add_i32 s7, s5, 0xff800000
	buffer_load_dwordx4 v[6:9], v221, s[16:19], s7 offen
	buffer_load_dwordx4 v[2:5], v221, s[16:19], s5 offen
	s_add_i32 s7, s22, 1
	v_cmp_gt_i32_e64 s[10:11], s22, v244
	v_cmp_le_i32_e32 vcc, s22, v244
	s_and_saveexec_b64 s[44:45], vcc
	s_cbranch_execz .LBB0_674
	s_bitcmp1_b32 s22, 0
	s_cselect_b32 s22, 0xac00, 0
	s_add_i32 s22, s22, 0
	v_add_u32_e32 v14, s22, v223
	v_add_u32_e32 v14, v14, v204
	ds_read_b128 v[168:171], v14
	ds_read_b128 v[172:175], v14 offset:32
	ds_read_b128 v[176:179], v14 offset:64
	ds_read_b128 v[180:183], v14 offset:96
	ds_read_b128 v[184:187], v14 offset:128
	ds_read_b128 v[188:191], v14 offset:160
	ds_read_b128 v[192:195], v14 offset:192
	ds_read_b128 v[196:199], v14 offset:224
	v_xor_b32_e32 v80, 0x80000000, v1
	v_mov_b32_e32 v81, v80
	v_mov_b64_e32 v[96:97], v[80:81]
	v_mov_b64_e32 v[98:99], v[80:81]
	v_mov_b64_e32 v[100:101], v[80:81]
	v_mov_b64_e32 v[102:103], v[80:81]
	v_mov_b64_e32 v[104:105], v[80:81]
	v_mov_b64_e32 v[106:107], v[80:81]
	v_mov_b64_e32 v[108:109], v[80:81]
	v_mov_b64_e32 v[110:111], v[80:81]
	s_waitcnt lgkmcnt(7)
	s_nop 0
	v_mfma_f32_32x32x16_bf16 v[96:111], v[168:171], v[112:115], v[96:111]
	s_waitcnt lgkmcnt(6)
	v_mfma_f32_32x32x16_bf16 v[96:111], v[172:175], v[116:119], v[96:111]
	s_waitcnt lgkmcnt(5)
	v_mfma_f32_32x32x16_bf16 v[96:111], v[176:179], v[120:123], v[96:111]
	s_waitcnt lgkmcnt(4)
	v_mfma_f32_32x32x16_bf16 v[96:111], v[180:183], v[124:127], v[96:111]
	ds_read_b128 v[82:85], v14 offset:256
	ds_read_b128 v[86:89], v14 offset:288
	ds_read_b128 v[90:93], v14 offset:320
	ds_read_b128 v[168:171], v14 offset:352
	s_waitcnt lgkmcnt(7)
	v_mfma_f32_32x32x16_bf16 v[96:111], v[184:187], v[128:131], v[96:111]
	s_waitcnt lgkmcnt(6)
	v_mfma_f32_32x32x16_bf16 v[96:111], v[188:191], v[132:135], v[96:111]
	s_waitcnt lgkmcnt(5)
	v_mfma_f32_32x32x16_bf16 v[96:111], v[192:195], v[136:139], v[96:111]
	s_waitcnt lgkmcnt(4)
	v_mfma_f32_32x32x16_bf16 v[96:111], v[196:199], v[140:143], v[96:111]
	s_waitcnt lgkmcnt(3)
	v_mfma_f32_32x32x16_bf16 v[96:111], v[82:85], v[148:151], v[96:111]
	s_waitcnt lgkmcnt(2)
	v_mfma_f32_32x32x16_bf16 v[96:111], v[86:89], v[156:159], v[96:111]
	s_waitcnt lgkmcnt(1)
	v_mfma_f32_32x32x16_bf16 v[96:111], v[90:93], v[144:147], v[96:111]
	s_waitcnt lgkmcnt(0)
	v_mfma_f32_32x32x16_bf16 v[96:111], v[168:171], v[152:155], v[96:111]
	ds_read_b128 v[196:199], v14 offset:12800
	ds_read_b128 v[192:195], v14 offset:12832
	ds_read_b128 v[188:191], v14 offset:12864
	ds_read_b128 v[184:187], v14 offset:12896
	ds_read_b128 v[180:183], v14 offset:12928
	ds_read_b128 v[176:179], v14 offset:12960
	ds_read_b128 v[172:175], v14 offset:12992
	ds_read_b128 v[168:171], v14 offset:13024
	s_nop 3
	v_max3_f32 v15, v96, v97, v98
	v_max3_f32 v81, v99, v100, v101
	v_max3_f32 v82, v102, v103, v104
	v_max3_f32 v83, v105, v106, v107
	v_max3_f32 v84, v108, v109, v110
	v_max3_f32 v15, v15, v81, v111
	v_max3_f32 v15, v15, v82, v83
	v_max_f32_e32 v15, v15, v84
	v_mov_b32_e32 v81, v15
	s_nop 1
	v_permlane32_swap_b32_e32 v81, v15
	v_max_f32_e32 v15, v15, v81
	v_cmp_lt_f32_e32 vcc, s47, v15
	s_cbranch_vccz .LBB0_671
	v_max_f32_e32 v15, v15, v15
	v_max_f32_e32 v80, 0, v15
	v_exp_f32_e64 v82, -v80
	v_add_f32_e32 v1, v1, v80
	v_pk_add_f32 v[96:97], v[96:97], v[80:81] op_sel_hi:[1,0] neg_lo:[0,1] neg_hi:[0,1]
	v_pk_add_f32 v[98:99], v[98:99], v[80:81] op_sel_hi:[1,0] neg_lo:[0,1] neg_hi:[0,1]
	v_pk_mul_f32 v[78:79], v[78:79], v[82:83] op_sel_hi:[1,0]
	v_pk_mul_f32 v[76:77], v[76:77], v[82:83] op_sel_hi:[1,0]
	v_pk_mul_f32 v[74:75], v[74:75], v[82:83] op_sel_hi:[1,0]
	v_pk_mul_f32 v[72:73], v[72:73], v[82:83] op_sel_hi:[1,0]
	v_pk_mul_f32 v[70:71], v[70:71], v[82:83] op_sel_hi:[1,0]
	v_pk_mul_f32 v[68:69], v[68:69], v[82:83] op_sel_hi:[1,0]
	v_pk_mul_f32 v[66:67], v[66:67], v[82:83] op_sel_hi:[1,0]
	v_pk_mul_f32 v[64:65], v[64:65], v[82:83] op_sel_hi:[1,0]
	v_pk_mul_f32 v[62:63], v[62:63], v[82:83] op_sel_hi:[1,0]
	v_pk_mul_f32 v[60:61], v[60:61], v[82:83] op_sel_hi:[1,0]
	v_pk_mul_f32 v[58:59], v[58:59], v[82:83] op_sel_hi:[1,0]
	v_pk_mul_f32 v[56:57], v[56:57], v[82:83] op_sel_hi:[1,0]
	v_pk_mul_f32 v[54:55], v[54:55], v[82:83] op_sel_hi:[1,0]
	v_pk_mul_f32 v[52:53], v[52:53], v[82:83] op_sel_hi:[1,0]
	v_pk_mul_f32 v[50:51], v[50:51], v[82:83] op_sel_hi:[1,0]
	v_pk_mul_f32 v[48:49], v[48:49], v[82:83] op_sel_hi:[1,0]
	v_pk_mul_f32 v[46:47], v[46:47], v[82:83] op_sel_hi:[1,0]
	v_pk_mul_f32 v[44:45], v[44:45], v[82:83] op_sel_hi:[1,0]
	v_pk_mul_f32 v[42:43], v[42:43], v[82:83] op_sel_hi:[1,0]
	v_pk_mul_f32 v[40:41], v[40:41], v[82:83] op_sel_hi:[1,0]
	v_pk_mul_f32 v[38:39], v[38:39], v[82:83] op_sel_hi:[1,0]
	v_pk_mul_f32 v[36:37], v[36:37], v[82:83] op_sel_hi:[1,0]
	v_pk_mul_f32 v[34:35], v[34:35], v[82:83] op_sel_hi:[1,0]
	v_pk_mul_f32 v[32:33], v[32:33], v[82:83] op_sel_hi:[1,0]
	v_pk_mul_f32 v[30:31], v[30:31], v[82:83] op_sel_hi:[1,0]
	v_pk_mul_f32 v[28:29], v[28:29], v[82:83] op_sel_hi:[1,0]
	v_pk_mul_f32 v[26:27], v[26:27], v[82:83] op_sel_hi:[1,0]
	v_pk_mul_f32 v[24:25], v[24:25], v[82:83] op_sel_hi:[1,0]
	v_pk_mul_f32 v[22:23], v[22:23], v[82:83] op_sel_hi:[1,0]
	v_pk_mul_f32 v[20:21], v[20:21], v[82:83] op_sel_hi:[1,0]
	v_pk_mul_f32 v[18:19], v[18:19], v[82:83] op_sel_hi:[1,0]
	v_pk_mul_f32 v[16:17], v[16:17], v[82:83] op_sel_hi:[1,0]
	v_pk_add_f32 v[100:101], v[100:101], v[80:81] op_sel_hi:[1,0] neg_lo:[0,1] neg_hi:[0,1]
	v_pk_add_f32 v[102:103], v[102:103], v[80:81] op_sel_hi:[1,0] neg_lo:[0,1] neg_hi:[0,1]
	v_pk_add_f32 v[104:105], v[104:105], v[80:81] op_sel_hi:[1,0] neg_lo:[0,1] neg_hi:[0,1]
	v_pk_add_f32 v[106:107], v[106:107], v[80:81] op_sel_hi:[1,0] neg_lo:[0,1] neg_hi:[0,1]
	v_pk_add_f32 v[108:109], v[108:109], v[80:81] op_sel_hi:[1,0] neg_lo:[0,1] neg_hi:[0,1]
	v_pk_add_f32 v[110:111], v[110:111], v[80:81] op_sel_hi:[1,0] neg_lo:[0,1] neg_hi:[0,1]
	v_mul_f32_e32 v216, v216, v82
	v_xor_b32_e32 v80, 0x80000000, v1
; template <int MODE> __device__ __forceinline__ void attn_phase(LAS unsigned char* lds, const bf16_t* Q, const bf16_t* KF, const bf16_t* VT, bf16_t* O, const int* positions, const float* gq, int G, int bid) {
;     ...
;                     if (__any(mx > 6.0f)) AT_RESCALE(_Pragma("unroll") for (int i = 0; i < 16; ++i) s0[i] -= d_;);
; #pragma unroll
;                     for (int i = 0; i < 16; ++i) s1[i] = -mrun;
;                     __builtin_amdgcn_sched_barrier(0);
;                     float ps = 0.f;
; #pragma unroll
;                     for (int kk = 0; kk < 4; ++kk) s1 = __builtin_amdgcn_mfma_f32_32x32x16_bf16(fr[kk], qf[kk], s1, 0, 0, 0);
; #pragma unroll
;                     for (int i = 0; i < 5; ++i) { s0[i] = __builtin_amdgcn_exp2f(s0[i]); ps += s0[i]; }
; #pragma unroll
;                     for (int g = 0; g < 4; ++g) { __builtin_amdgcn_sched_group_barrier(0x008, 1, 0); __builtin_amdgcn_sched_group_barrier(0x002, 3, 0); }
;                     __builtin_amdgcn_sched_barrier(0);
; #pragma unroll
;                     for (int kk = 8; kk < 12; ++kk) fr2[kk - 8] = *(const LAS bf16x8*)(kb + (32 + lq) * AT_KP + (16 * kk + 8 * hi) * 2);
;                     __builtin_amdgcn_sched_barrier(0);
; #pragma unroll
;                     for (int kk = 4; kk < 8; ++kk) s1 = __builtin_amdgcn_mfma_f32_32x32x16_bf16(fr[kk], qf[kk], s1, 0, 0, 0);
; #pragma unroll
;                     for (int kk = 8; kk < 12; ++kk) s1 = __builtin_amdgcn_mfma_f32_32x32x16_bf16(fr2[kk - 8], qf[kk], s1, 0, 0, 0);
; #pragma unroll
;                     for (int i = 5; i < 16; ++i) { s0[i] = __builtin_amdgcn_exp2f(s0[i]); ps += s0[i]; }
; #pragma unroll
;                     for (int g = 0; g < 8; ++g) { __builtin_amdgcn_sched_group_barrier(0x008, 1, 0); __builtin_amdgcn_sched_group_barrier(0x002, 3, 0); }
;                     __builtin_amdgcn_sched_barrier(0);
;                     bf16x8 va[8];
; #pragma unroll
;                     for (int ks = 0; ks < 2; ++ks)
; #pragma unroll
;                         for (int db = 0; db < 4; ++db) va[ks * 4 + db] = *(const LAS bf16x8*)(vb + (32 * db + lq) * AT_VP + (16 * ks + 8 * hi) * 2);
;                     __builtin_amdgcn_sched_barrier(0);
;                     mx = fmaxf(fmaxf(s1[0], s1[1]), fmaxf(s1[2], s1[3]));
; #pragma unroll
;                     for (int i = 4; i < 16; i += 2) mx = fmaxf(mx, fmaxf(s1[i], s1[i + 1]));
.LBB0_671:
	v_mov_b32_e32 v81, v80
	v_mov_b64_e32 v[82:83], v[80:81]
	v_mov_b64_e32 v[84:85], v[80:81]
	v_mov_b64_e32 v[86:87], v[80:81]
	v_mov_b64_e32 v[88:89], v[80:81]
	v_mov_b64_e32 v[90:91], v[80:81]
	v_mov_b64_e32 v[92:93], v[80:81]
	v_mov_b64_e32 v[94:95], v[80:81]
	s_waitcnt lgkmcnt(7)
	s_nop 0
	v_mfma_f32_32x32x16_bf16 v[80:95], v[196:199], v[112:115], v[80:95]
	v_exp_f32_e32 v196, v96
	v_exp_f32_e32 v197, v97
	v_add_f32_e32 v15, 0, v196
	v_add_f32_e32 v15, v197, v15
	s_waitcnt lgkmcnt(6)
	v_mfma_f32_32x32x16_bf16 v[80:95], v[192:195], v[116:119], v[80:95]
	v_exp_f32_e32 v194, v98
	v_exp_f32_e32 v195, v99
	v_exp_f32_e32 v192, v100
	v_add_f32_e32 v15, v194, v15
	v_add_f32_e32 v15, v195, v15
	v_add_f32_e32 v15, v192, v15
	s_waitcnt lgkmcnt(5)
	v_mfma_f32_32x32x16_bf16 v[80:95], v[188:191], v[120:123], v[80:95]
	s_waitcnt lgkmcnt(4)
	v_mfma_f32_32x32x16_bf16 v[80:95], v[184:187], v[124:127], v[80:95]
	ds_read_b128 v[96:99], v14 offset:13056
	ds_read_b128 v[188:191], v14 offset:13088
	ds_read_b128 v[246:249], v14 offset:13120
	ds_read_b128 v[250:253], v14 offset:13152
	s_waitcnt lgkmcnt(7)
	v_mfma_f32_32x32x16_bf16 v[80:95], v[180:183], v[128:131], v[80:95]
	v_exp_f32_e32 v193, v101
	v_exp_f32_e32 v198, v102
	v_exp_f32_e32 v199, v103
	v_exp_f32_e32 v186, v104
	v_exp_f32_e32 v187, v105
	v_add_f32_e32 v14, v193, v15
	v_add_f32_e32 v14, v198, v14
	s_waitcnt lgkmcnt(6)
	v_mfma_f32_32x32x16_bf16 v[80:95], v[176:179], v[132:135], v[80:95]
	v_add_f32_e32 v14, v199, v14
	v_add_f32_e32 v14, v186, v14
	v_add_f32_e32 v14, v187, v14
	v_exp_f32_e32 v184, v110
	v_exp_f32_e32 v185, v111
	s_waitcnt lgkmcnt(5)
	v_mfma_f32_32x32x16_bf16 v[80:95], v[172:175], v[136:139], v[80:95]
	s_waitcnt lgkmcnt(4)
	v_mfma_f32_32x32x16_bf16 v[80:95], v[168:171], v[140:143], v[80:95]
	s_waitcnt lgkmcnt(3)
	v_mfma_f32_32x32x16_bf16 v[80:95], v[96:99], v[148:151], v[80:95]
	s_waitcnt lgkmcnt(2)
	v_mfma_f32_32x32x16_bf16 v[80:95], v[188:191], v[156:159], v[80:95]
	v_exp_f32_e32 v190, v106
	v_exp_f32_e32 v191, v107
	v_exp_f32_e32 v188, v108
	v_exp_f32_e32 v189, v109
	v_add_f32_e32 v14, v190, v14
	v_add_f32_e32 v14, v191, v14
	v_add_f32_e32 v14, v188, v14
	s_waitcnt lgkmcnt(1)
	v_mfma_f32_32x32x16_bf16 v[80:95], v[246:249], v[144:147], v[80:95]
	v_add_f32_e32 v14, v189, v14
	v_add_f32_e32 v14, v184, v14
	v_add_f32_e32 v14, v185, v14
	s_waitcnt lgkmcnt(0)
	v_mfma_f32_32x32x16_bf16 v[80:95], v[250:253], v[152:155], v[80:95]
	v_add_u32_e32 v15, s22, v204
	v_add_u32_e32 v245, v15, v242
	ds_read_b128 v[180:183], v245 offset:25600
	ds_read_b128 v[100:103], v245 offset:25632
	ds_read_b128 v[176:179], v245 offset:30208
	ds_read_b128 v[104:107], v245 offset:30240
	ds_read_b128 v[172:175], v245 offset:34816
	ds_read_b128 v[108:111], v245 offset:34848
	ds_read_b128 v[168:171], v245 offset:39424
	ds_read_b128 v[96:99], v245 offset:39456
	s_nop 1
	v_max3_f32 v15, v80, v81, v82
	v_max3_f32 v217, v83, v84, v85
	v_max3_f32 v246, v86, v87, v88
	v_max3_f32 v247, v89, v90, v91
	v_max3_f32 v248, v92, v93, v94
	v_max3_f32 v15, v15, v217, v95
	v_max3_f32 v15, v15, v246, v247
	v_max_f32_e32 v15, v15, v248
	v_mov_b32_e32 v217, v15
	s_nop 1
	v_permlane32_swap_b32_e32 v217, v15
	v_max_f32_e32 v15, v15, v217
	v_cmp_lt_f32_e32 vcc, s47, v15
	s_cbranch_vccz .LBB0_673
	v_max_f32_e32 v15, v15, v15
	v_max_f32_e32 v246, 0, v15
	v_exp_f32_e64 v248, -v246
	v_add_f32_e32 v1, v1, v246
	v_pk_add_f32 v[80:81], v[80:81], v[246:247] op_sel_hi:[1,0] neg_lo:[0,1] neg_hi:[0,1]
	v_pk_add_f32 v[82:83], v[82:83], v[246:247] op_sel_hi:[1,0] neg_lo:[0,1] neg_hi:[0,1]
	v_pk_mul_f32 v[78:79], v[78:79], v[248:249] op_sel_hi:[1,0]
	v_pk_mul_f32 v[76:77], v[76:77], v[248:249] op_sel_hi:[1,0]
	v_pk_mul_f32 v[74:75], v[74:75], v[248:249] op_sel_hi:[1,0]
	v_pk_mul_f32 v[72:73], v[72:73], v[248:249] op_sel_hi:[1,0]
	v_pk_mul_f32 v[70:71], v[70:71], v[248:249] op_sel_hi:[1,0]
	v_pk_mul_f32 v[68:69], v[68:69], v[248:249] op_sel_hi:[1,0]
	v_pk_mul_f32 v[66:67], v[66:67], v[248:249] op_sel_hi:[1,0]
	v_pk_mul_f32 v[64:65], v[64:65], v[248:249] op_sel_hi:[1,0]
	v_pk_mul_f32 v[62:63], v[62:63], v[248:249] op_sel_hi:[1,0]
	v_pk_mul_f32 v[60:61], v[60:61], v[248:249] op_sel_hi:[1,0]
	v_pk_mul_f32 v[58:59], v[58:59], v[248:249] op_sel_hi:[1,0]
	v_pk_mul_f32 v[56:57], v[56:57], v[248:249] op_sel_hi:[1,0]
	v_pk_mul_f32 v[54:55], v[54:55], v[248:249] op_sel_hi:[1,0]
	v_pk_mul_f32 v[52:53], v[52:53], v[248:249] op_sel_hi:[1,0]
	v_pk_mul_f32 v[50:51], v[50:51], v[248:249] op_sel_hi:[1,0]
	v_pk_mul_f32 v[48:49], v[48:49], v[248:249] op_sel_hi:[1,0]
	v_pk_mul_f32 v[46:47], v[46:47], v[248:249] op_sel_hi:[1,0]
	v_pk_mul_f32 v[44:45], v[44:45], v[248:249] op_sel_hi:[1,0]
	v_pk_mul_f32 v[42:43], v[42:43], v[248:249] op_sel_hi:[1,0]
	v_pk_mul_f32 v[40:41], v[40:41], v[248:249] op_sel_hi:[1,0]
	v_pk_mul_f32 v[38:39], v[38:39], v[248:249] op_sel_hi:[1,0]
	v_pk_mul_f32 v[36:37], v[36:37], v[248:249] op_sel_hi:[1,0]
	v_pk_mul_f32 v[34:35], v[34:35], v[248:249] op_sel_hi:[1,0]
	v_pk_mul_f32 v[32:33], v[32:33], v[248:249] op_sel_hi:[1,0]
	v_pk_mul_f32 v[30:31], v[30:31], v[248:249] op_sel_hi:[1,0]
	v_pk_mul_f32 v[28:29], v[28:29], v[248:249] op_sel_hi:[1,0]
	v_pk_mul_f32 v[26:27], v[26:27], v[248:249] op_sel_hi:[1,0]
	v_pk_mul_f32 v[24:25], v[24:25], v[248:249] op_sel_hi:[1,0]
	v_pk_mul_f32 v[22:23], v[22:23], v[248:249] op_sel_hi:[1,0]
	v_pk_mul_f32 v[20:21], v[20:21], v[248:249] op_sel_hi:[1,0]
	v_pk_mul_f32 v[18:19], v[18:19], v[248:249] op_sel_hi:[1,0]
	v_pk_mul_f32 v[16:17], v[16:17], v[248:249] op_sel_hi:[1,0]
	v_mul_f32_e32 v216, v216, v248
	v_pk_add_f32 v[84:85], v[84:85], v[246:247] op_sel_hi:[1,0] neg_lo:[0,1] neg_hi:[0,1]
	v_pk_add_f32 v[86:87], v[86:87], v[246:247] op_sel_hi:[1,0] neg_lo:[0,1] neg_hi:[0,1]
	v_pk_add_f32 v[88:89], v[88:89], v[246:247] op_sel_hi:[1,0] neg_lo:[0,1] neg_hi:[0,1]
	v_pk_add_f32 v[90:91], v[90:91], v[246:247] op_sel_hi:[1,0] neg_lo:[0,1] neg_hi:[0,1]
	v_pk_add_f32 v[92:93], v[92:93], v[246:247] op_sel_hi:[1,0] neg_lo:[0,1] neg_hi:[0,1]
	v_pk_mul_f32 v[184:185], v[184:185], v[248:249] op_sel_hi:[1,0]
	v_pk_mul_f32 v[188:189], v[188:189], v[248:249] op_sel_hi:[1,0]
	v_pk_mul_f32 v[190:191], v[190:191], v[248:249] op_sel_hi:[1,0]
	v_pk_mul_f32 v[186:187], v[186:187], v[248:249] op_sel_hi:[1,0]
	v_pk_mul_f32 v[198:199], v[198:199], v[248:249] op_sel_hi:[1,0]
	v_pk_mul_f32 v[192:193], v[192:193], v[248:249] op_sel_hi:[1,0]
	v_pk_mul_f32 v[194:195], v[194:195], v[248:249] op_sel_hi:[1,0]
	v_pk_mul_f32 v[196:197], v[196:197], v[248:249] op_sel_hi:[1,0]
	v_pk_add_f32 v[94:95], v[94:95], v[246:247] op_sel_hi:[1,0] neg_lo:[0,1] neg_hi:[0,1]
	v_mul_f32_e32 v14, v14, v248
; #define LAS __attribute__((address_space(3)))
; __device__ __forceinline__ unsigned pk2(float lo, float hi) { return pg8::cvt_pk_bf16(lo, hi); }
; template <int MODE> __device__ __forceinline__ void attn_phase(LAS unsigned char* lds, const bf16_t* Q, const bf16_t* KF, const bf16_t* VT, bf16_t* O, const int* positions, const float* gq, int G, int bid) {
;     ...
;                     bf16x8 pb[2];
; #pragma unroll
;                     for (int ks = 0; ks < 2; ++ks)
; #pragma unroll
;                         for (int q = 0; q < 4; ++q) { const unsigned pk = pk2(s0[8 * ks + 2 * q], s0[8 * ks + 2 * q + 1]); pb[ks][2 * q] = (short)(pk & 0xffff); pb[ks][2 * q + 1] = (short)(pk >> 16); }
;                     __builtin_amdgcn_sched_barrier(0);
; #pragma unroll
;                     for (int ks = 0; ks < 2; ++ks)
; #pragma unroll
;                         for (int db = 0; db < 4; ++db) o[db] = __builtin_amdgcn_mfma_f32_32x32x16_bf16(va[ks * 4 + db], pb[ks], o[db], 0, 0, 0);
;                     float ps1 = 0.f;
; #pragma unroll
;                     for (int i = 0; i < 16; ++i) { s1[i] = __builtin_amdgcn_exp2f(s1[i]); ps1 += s1[i]; }
; #pragma unroll
;                     for (int g = 0; g < 8; ++g) { __builtin_amdgcn_sched_group_barrier(0x008, 1, 0); __builtin_amdgcn_sched_group_barrier(0x002, 4, 0); }
;                     __builtin_amdgcn_sched_barrier(0);
;                     lsum += ps1;
; #pragma unroll
;                     for (int ks = 0; ks < 2; ++ks)
; #pragma unroll
;                         for (int db = 0; db < 4; ++db) va[ks * 4 + db] = *(const LAS bf16x8*)(vb + (32 * db + lq) * AT_VP + (16 * (ks + 2) + 8 * hi) * 2);
;                     if (more && MODE < 3) AT_LSTORE((kt + 1) & 1);
;                     __builtin_amdgcn_sched_barrier(0);
; #pragma unroll
;                     for (int ks = 0; ks < 2; ++ks)
; #pragma unroll
;                         for (int q = 0; q < 4; ++q) { const unsigned pk = pk2(s1[8 * ks + 2 * q], s1[8 * ks + 2 * q + 1]); pb[ks][2 * q] = (short)(pk & 0xffff); pb[ks][2 * q + 1] = (short)(pk >> 16); }
;                     __builtin_amdgcn_sched_barrier(0);
; #pragma unroll
;                     for (int ks = 0; ks < 2; ++ks)
; #pragma unroll
;                         for (int db = 0; db < 4; ++db) o[db] = __builtin_amdgcn_mfma_f32_32x32x16_bf16(va[ks * 4 + db], pb[ks], o[db], 0, 0, 0);
.LBB0_673:
	v_cvt_pk_bf16_f32 v246, v196, v197
	v_cvt_pk_bf16_f32 v247, v194, v195
	v_cvt_pk_bf16_f32 v248, v192, v193
	v_cvt_pk_bf16_f32 v249, v198, v199
	v_cvt_pk_bf16_f32 v186, v186, v187
	v_cvt_pk_bf16_f32 v187, v190, v191
	v_cvt_pk_bf16_f32 v188, v188, v189
	v_cvt_pk_bf16_f32 v189, v184, v185
	s_nop 0
	s_waitcnt lgkmcnt(7)
	v_mfma_f32_32x32x16_bf16 v[64:79], v[180:183], v[246:249], v[64:79]
	v_exp_f32_e32 v180, v80
	v_exp_f32_e32 v181, v81
	v_exp_f32_e32 v182, v82
	v_exp_f32_e32 v183, v83
	v_add_f32_e32 v15, 0, v180
	v_add_f32_e32 v15, v181, v15
	v_add_f32_e32 v15, v182, v15
	v_add_f32_e32 v15, v183, v15
	s_waitcnt lgkmcnt(5)
	v_mfma_f32_32x32x16_bf16 v[48:63], v[176:179], v[246:249], v[48:63]
	v_exp_f32_e32 v176, v84
	v_exp_f32_e32 v177, v85
	v_exp_f32_e32 v178, v86
	v_exp_f32_e32 v179, v87
	v_add_f32_e32 v15, v176, v15
	v_add_f32_e32 v15, v177, v15
	v_add_f32_e32 v15, v178, v15
	v_add_f32_e32 v15, v179, v15
	s_waitcnt lgkmcnt(3)
	v_mfma_f32_32x32x16_bf16 v[32:47], v[172:175], v[246:249], v[32:47]
	v_exp_f32_e32 v172, v88
	v_exp_f32_e32 v173, v89
	v_exp_f32_e32 v174, v90
	v_exp_f32_e32 v175, v91
	v_add_f32_e32 v15, v172, v15
	v_add_f32_e32 v15, v173, v15
	v_add_f32_e32 v15, v174, v15
	v_add_f32_e32 v15, v175, v15
	s_waitcnt lgkmcnt(1)
	v_mfma_f32_32x32x16_bf16 v[16:31], v[168:171], v[246:249], v[16:31]
	v_exp_f32_e32 v184, v92
	v_exp_f32_e32 v185, v93
	v_exp_f32_e32 v190, v94
	v_add_f32_e32 v15, v184, v15
	v_add_f32_e32 v15, v185, v15
	v_add_f32_e32 v217, v190, v15
	v_mfma_f32_32x32x16_bf16 v[64:79], v[100:103], v[186:189], v[64:79]
	v_exp_f32_e32 v15, v95
	v_mfma_f32_32x32x16_bf16 v[48:63], v[104:107], v[186:189], v[48:63]
	v_mfma_f32_32x32x16_bf16 v[32:47], v[108:111], v[186:189], v[32:47]
	s_waitcnt lgkmcnt(0)
	v_mfma_f32_32x32x16_bf16 v[16:31], v[96:99], v[186:189], v[16:31]
	s_bitcmp1_b32 s7, 0
	s_cselect_b32 s22, 0xac00, 0
	ds_read_b128 v[80:83], v245 offset:25664
	ds_read_b128 v[84:87], v245 offset:25696
	ds_read_b128 v[88:91], v245 offset:30272
	ds_read_b128 v[92:95], v245 offset:30304
	ds_read_b128 v[96:99], v245 offset:34880
	ds_read_b128 v[100:103], v245 offset:34912
	ds_read_b128 v[104:107], v245 offset:39488
	ds_read_b128 v[108:111], v245 offset:39520
	s_add_i32 s22, s22, 0
	v_pk_add_f32 v[168:169], v[14:15], v[216:217]
	v_add_u32_e32 v14, s22, v200
	s_waitcnt vmcnt(4)
	ds_write_b128 v14, v[10:13]
	s_waitcnt vmcnt(3)
	ds_write_b128 v14, v[160:163] offset:128
	s_waitcnt vmcnt(2)
	ds_write_b128 v14, v[164:167] offset:256
	v_add_u32_e32 v14, s22, v222
	v_add_f32_e32 v216, v168, v169
	v_add_u32_e32 v168, 0x6000, v14
	v_add_u32_e32 v14, 0x8800, v14
	s_waitcnt vmcnt(1)
	ds_write2_b64 v168, v[6:7], v[8:9] offset0:128 offset1:130
	s_waitcnt vmcnt(0)
	ds_write2_b64 v14, v[2:3], v[4:5] offset1:2
	v_cvt_pk_bf16_f32 v168, v180, v181
	v_cvt_pk_bf16_f32 v169, v182, v183
	v_cvt_pk_bf16_f32 v170, v176, v177
	v_cvt_pk_bf16_f32 v171, v178, v179
	v_cvt_pk_bf16_f32 v172, v172, v173
	v_cvt_pk_bf16_f32 v173, v174, v175
	v_cvt_pk_bf16_f32 v174, v184, v185
	v_cvt_pk_bf16_f32 v175, v190, v15
	s_waitcnt lgkmcnt(12)
	v_mfma_f32_32x32x16_bf16 v[64:79], v[80:83], v[168:171], v[64:79]
	s_waitcnt lgkmcnt(10)
	v_mfma_f32_32x32x16_bf16 v[48:63], v[88:91], v[168:171], v[48:63]
	s_waitcnt lgkmcnt(8)
	v_mfma_f32_32x32x16_bf16 v[32:47], v[96:99], v[168:171], v[32:47]
	s_waitcnt lgkmcnt(6)
	v_mfma_f32_32x32x16_bf16 v[16:31], v[104:107], v[168:171], v[16:31]
	v_mfma_f32_32x32x16_bf16 v[64:79], v[84:87], v[172:175], v[64:79]
	v_mfma_f32_32x32x16_bf16 v[48:63], v[92:95], v[172:175], v[48:63]
	v_mfma_f32_32x32x16_bf16 v[32:47], v[100:103], v[172:175], v[32:47]
	s_waitcnt lgkmcnt(5)
	v_mfma_f32_32x32x16_bf16 v[16:31], v[108:111], v[172:175], v[16:31]

; __device__ __forceinline__ const float* karg_in(int i) { karg_ptr_t kp = (karg_ptr_t)__builtin_amdgcn_kernarg_segment_ptr(); asm volatile("" : "+s"(kp)); return *(const float* __attribute__((address_space(4))) const*)(kp + 8 * i); }
; #define OUTP karg_out()
; __global__ void __launch_bounds__(512, 2) fwd_megakernel(Params p) {
;     ...
;     { FRESH_LANE_IDS;
;     for (int m = gw; m < T; m += NGW) {
;         const u32x2* xr = (const u32x2*)(H3 + (size_t)m * DM) + lane; f32x4* orow = (f32x4*)(OUTP + (size_t)m * DM) + lane; const f32x4* gr = (const f32x4*)karg_in(23) + lane;
;         f32x4 v[4]; float s = 0.f;
; #pragma unroll
;         for (int j = 0; j < 4; ++j) { const u32x2 a = xr[64 * j];
.LBB0_909:
	s_or_b64 exec, exec, s[2:3]
	s_barrier
	v_lshrrev_b32_e32 v0, 6, v218
	v_and_b32_e32 v6, 63, v218
	s_load_dwordx2 s[16:17], s[0:1], 0xc8
	s_load_dwordx2 s[10:11], s[0:1], 0xc0
	s_load_dwordx2 s[8:9], s[0:1], 0xb8
	v_readfirstlane_b32 s4, v0
	v_lshlrev_b32_e32 v5, 4, v6
	v_lshlrev_b32_e32 v7, 3, v6
	s_lshl_b32 s22, s28, 11
	s_lshl_b32 s23, s28, 12
	s_add_i32 s4, s4, s70
	s_cmp_ge_i32 s4, 0x10000
	s_cbranch_scc1 .Lfn_end
	s_waitcnt lgkmcnt(0)
	s_add_u32 s16, s16, 0x22000000
	s_addc_u32 s17, s17, 0
	s_lshl_b32 s5, s4, 11
	s_add_u32 s18, s16, s5
	s_addc_u32 s19, s17, 0
	s_lshl_b32 s5, s4, 12
	s_add_u32 s20, s10, s5
	s_addc_u32 s21, s11, 0
	global_load_dwordx4 v[60:63], v5, s[8:9]
	global_load_dwordx4 v[64:67], v5, s[8:9] offset:1024
	global_load_dwordx4 v[68:71], v5, s[8:9] offset:2048
	global_load_dwordx4 v[72:75], v5, s[8:9] offset:3072
	global_load_dwordx2 v[20:21], v7, s[18:19]
	global_load_dwordx2 v[22:23], v7, s[18:19] offset:512
	global_load_dwordx2 v[24:25], v7, s[18:19] offset:1024
	global_load_dwordx2 v[26:27], v7, s[18:19] offset:1536
	s_add_i32 s4, s4, s28
	s_cmp_lt_i32 s4, 0x10000
	s_cselect_b32 s25, 1, 0
	s_cselect_b32 s24, s22, 0
	s_add_u32 s26, s18, s24
	s_addc_u32 s27, s19, 0
	global_load_dwordx2 v[28:29], v7, s[26:27]
	global_load_dwordx2 v[30:31], v7, s[26:27] offset:512
	global_load_dwordx2 v[32:33], v7, s[26:27] offset:1024
	global_load_dwordx2 v[34:35], v7, s[26:27] offset:1536
	s_waitcnt vmcnt(4)
	s_branch .Lfn_A_compute
.Lfn_A_top:
	s_add_i32 s4, s4, s28
	s_cmp_lt_i32 s4, 0x10000
	s_cselect_b32 s25, 1, 0
	s_cselect_b32 s24, s22, 0
	s_add_u32 s26, s18, s24
	s_addc_u32 s27, s19, 0
	global_load_dwordx2 v[28:29], v7, s[26:27]
	global_load_dwordx2 v[30:31], v7, s[26:27] offset:512
	global_load_dwordx2 v[32:33], v7, s[26:27] offset:1024
	global_load_dwordx2 v[34:35], v7, s[26:27] offset:1536
	s_waitcnt vmcnt(8)
; __device__ __forceinline__ const float* karg_in(int i) { karg_ptr_t kp = (karg_ptr_t)__builtin_amdgcn_kernarg_segment_ptr(); asm volatile("" : "+s"(kp)); return *(const float* __attribute__((address_space(4))) const*)(kp + 8 * i); }
; #define OUTP karg_out()
; __global__ void __launch_bounds__(512, 2) fwd_megakernel(Params p) {
;     ...
;     for (int m = gw; m < T; m += NGW) {
;         const u32x2* xr = (const u32x2*)(H3 + (size_t)m * DM) + lane; f32x4* orow = (f32x4*)(OUTP + (size_t)m * DM) + lane; const f32x4* gr = (const f32x4*)karg_in(23) + lane;
;         f32x4 v[4]; float s = 0.f;
; #pragma unroll
;         for (int j = 0; j < 4; ++j) { const u32x2 a = xr[64 * j];
;             v[j] = (f32x4){__uint_as_float(a.x << 16), __uint_as_float(a.x & 0xffff0000u), __uint_as_float(a.y << 16), __uint_as_float(a.y & 0xffff0000u)};
;             s += (v[j].x * v[j].x + v[j].y * v[j].y) + (v[j].z * v[j].z + v[j].w * v[j].w); }
;         const float r = rsqrtf(wave_sum(s) * (1.0f / DM) + EPS);
; #pragma unroll
;         for (int j = 0; j < 4; ++j) orow[64 * j] = v[j] * r * gr[64 * j];
;     } }
.Lfn_A_compute:
	v_lshlrev_b32_e32 v40, 16, v20
	v_and_b32_e32 v41, 0xffff0000, v20
	v_lshlrev_b32_e32 v42, 16, v21
	v_and_b32_e32 v43, 0xffff0000, v21
	v_lshlrev_b32_e32 v44, 16, v22
	v_and_b32_e32 v45, 0xffff0000, v22
	v_lshlrev_b32_e32 v46, 16, v23
	v_and_b32_e32 v47, 0xffff0000, v23
	v_lshlrev_b32_e32 v48, 16, v24
	v_and_b32_e32 v49, 0xffff0000, v24
	v_lshlrev_b32_e32 v50, 16, v25
	v_and_b32_e32 v51, 0xffff0000, v25
	v_lshlrev_b32_e32 v52, 16, v26
	v_and_b32_e32 v53, 0xffff0000, v26
	v_lshlrev_b32_e32 v54, 16, v27
	v_and_b32_e32 v55, 0xffff0000, v27
	v_pk_mul_f32 v[36:37], v[40:41], v[40:41]
	v_pk_fma_f32 v[36:37], v[42:43], v[42:43], v[36:37]
	v_pk_fma_f32 v[36:37], v[44:45], v[44:45], v[36:37]
	v_pk_fma_f32 v[36:37], v[46:47], v[46:47], v[36:37]
	v_pk_fma_f32 v[36:37], v[48:49], v[48:49], v[36:37]
	v_pk_fma_f32 v[36:37], v[50:51], v[50:51], v[36:37]
	v_pk_fma_f32 v[36:37], v[52:53], v[52:53], v[36:37]
	v_pk_fma_f32 v[36:37], v[54:55], v[54:55], v[36:37]
	v_add_f32_e32 v36, v36, v37
	s_nop 1
	v_add_f32_dpp v36, v36, v36 row_ror:8 row_mask:0xf bank_mask:0xf bound_ctrl:1
	s_nop 1
	v_add_f32_dpp v36, v36, v36 row_ror:4 row_mask:0xf bank_mask:0xf bound_ctrl:1
	s_nop 1
	v_add_f32_dpp v36, v36, v36 row_ror:2 row_mask:0xf bank_mask:0xf bound_ctrl:1
	s_nop 1
	v_add_f32_dpp v36, v36, v36 row_ror:1 row_mask:0xf bank_mask:0xf bound_ctrl:1
	s_nop 1
	v_readlane_b32 s12, v36, 0
	v_readlane_b32 s13, v36, 16
	v_readlane_b32 s14, v36, 32
	v_readlane_b32 s15, v36, 48
	v_mov_b32_e32 v38, 0x358637bd
	s_nop 1
	v_mov_b32_e32 v37, s12
	v_add_f32_e32 v37, s13, v37
	v_add_f32_e32 v37, s14, v37
	v_add_f32_e32 v37, s15, v37
	v_fmac_f32_e32 v38, 0x3a800000, v37
	v_rsq_f32_e32 v36, v38
	s_nop 1
	v_pk_mul_f32 v[40:41], v[36:37], v[40:41] op_sel_hi:[0,1]
	v_pk_mul_f32 v[42:43], v[36:37], v[42:43] op_sel_hi:[0,1]
	v_pk_mul_f32 v[44:45], v[36:37], v[44:45] op_sel_hi:[0,1]
	v_pk_mul_f32 v[46:47], v[36:37], v[46:47] op_sel_hi:[0,1]
	v_pk_mul_f32 v[48:49], v[36:37], v[48:49] op_sel_hi:[0,1]
	v_pk_mul_f32 v[50:51], v[36:37], v[50:51] op_sel_hi:[0,1]
	v_pk_mul_f32 v[52:53], v[36:37], v[52:53] op_sel_hi:[0,1]
	v_pk_mul_f32 v[54:55], v[36:37], v[54:55] op_sel_hi:[0,1]
	v_pk_mul_f32 v[40:41], v[40:41], v[60:61]
	v_pk_mul_f32 v[42:43], v[42:43], v[62:63]
	v_pk_mul_f32 v[44:45], v[44:45], v[64:65]
	v_pk_mul_f32 v[46:47], v[46:47], v[66:67]
	v_pk_mul_f32 v[48:49], v[48:49], v[68:69]
	v_pk_mul_f32 v[50:51], v[50:51], v[70:71]
	v_pk_mul_f32 v[52:53], v[52:53], v[72:73]
	v_pk_mul_f32 v[54:55], v[54:55], v[74:75]
	global_store_dwordx4 v5, v[40:43], s[20:21]
	global_store_dwordx4 v5, v[44:47], s[20:21] offset:1024
	global_store_dwordx4 v5, v[48:51], s[20:21] offset:2048
	global_store_dwordx4 v5, v[52:55], s[20:21] offset:3072
	s_cmp_eq_u32 s25, 0
	s_cbranch_scc1 .Lfn_end
	s_mov_b64 s[18:19], s[26:27]
	s_add_u32 s20, s20, s23
	s_addc_u32 s21, s21, 0
	s_add_i32 s4, s4, s28
	s_cmp_lt_i32 s4, 0x10000
	s_cselect_b32 s25, 1, 0
	s_cselect_b32 s24, s22, 0
	s_add_u32 s26, s18, s24
	s_addc_u32 s27, s19, 0
	global_load_dwordx2 v[20:21], v7, s[26:27]
	global_load_dwordx2 v[22:23], v7, s[26:27] offset:512
	global_load_dwordx2 v[24:25], v7, s[26:27] offset:1024
	global_load_dwordx2 v[26:27], v7, s[26:27] offset:1536
	s_waitcnt vmcnt(8)
	v_lshlrev_b32_e32 v40, 16, v28
	v_and_b32_e32 v41, 0xffff0000, v28
	v_lshlrev_b32_e32 v42, 16, v29
	v_and_b32_e32 v43, 0xffff0000, v29
	v_lshlrev_b32_e32 v44, 16, v30
	v_and_b32_e32 v45, 0xffff0000, v30
	v_lshlrev_b32_e32 v46, 16, v31
	v_and_b32_e32 v47, 0xffff0000, v31
	v_lshlrev_b32_e32 v48, 16, v32
	v_and_b32_e32 v49, 0xffff0000, v32
	v_lshlrev_b32_e32 v50, 16, v33
	v_and_b32_e32 v51, 0xffff0000, v33
	v_lshlrev_b32_e32 v52, 16, v34
	v_and_b32_e32 v53, 0xffff0000, v34
	v_lshlrev_b32_e32 v54, 16, v35
	v_and_b32_e32 v55, 0xffff0000, v35
	v_pk_mul_f32 v[36:37], v[40:41], v[40:41]
	v_pk_fma_f32 v[36:37], v[42:43], v[42:43], v[36:37]
	v_pk_fma_f32 v[36:37], v[44:45], v[44:45], v[36:37]
	v_pk_fma_f32 v[36:37], v[46:47], v[46:47], v[36:37]
	v_pk_fma_f32 v[36:37], v[48:49], v[48:49], v[36:37]
	v_pk_fma_f32 v[36:37], v[50:51], v[50:51], v[36:37]
	v_pk_fma_f32 v[36:37], v[52:53], v[52:53], v[36:37]
	v_pk_fma_f32 v[36:37], v[54:55], v[54:55], v[36:37]
	v_add_f32_e32 v36, v36, v37
	s_nop 1
	v_add_f32_dpp v36, v36, v36 row_ror:8 row_mask:0xf bank_mask:0xf bound_ctrl:1
	s_nop 1
	v_add_f32_dpp v36, v36, v36 row_ror:4 row_mask:0xf bank_mask:0xf bound_ctrl:1
	s_nop 1
	v_add_f32_dpp v36, v36, v36 row_ror:2 row_mask:0xf bank_mask:0xf bound_ctrl:1
	s_nop 1
	v_add_f32_dpp v36, v36, v36 row_ror:1 row_mask:0xf bank_mask:0xf bound_ctrl:1
	s_nop 1
	v_readlane_b32 s12, v36, 0
	v_readlane_b32 s13, v36, 16
	v_readlane_b32 s14, v36, 32
	v_readlane_b32 s15, v36, 48
	v_mov_b32_e32 v38, 0x358637bd
	s_nop 1
	v_mov_b32_e32 v37, s12
	v_add_f32_e32 v37, s13, v37
	v_add_f32_e32 v37, s14, v37
	v_add_f32_e32 v37, s15, v37
	v_fmac_f32_e32 v38, 0x3a800000, v37
	v_rsq_f32_e32 v36, v38
	s_nop 1
	v_pk_mul_f32 v[40:41], v[36:37], v[40:41] op_sel_hi:[0,1]
	v_pk_mul_f32 v[42:43], v[36:37], v[42:43] op_sel_hi:[0,1]
	v_pk_mul_f32 v[44:45], v[36:37], v[44:45] op_sel_hi:[0,1]
	v_pk_mul_f32 v[46:47], v[36:37], v[46:47] op_sel_hi:[0,1]
	v_pk_mul_f32 v[48:49], v[36:37], v[48:49] op_sel_hi:[0,1]
	v_pk_mul_f32 v[50:51], v[36:37], v[50:51] op_sel_hi:[0,1]
	v_pk_mul_f32 v[52:53], v[36:37], v[52:53] op_sel_hi:[0,1]
	v_pk_mul_f32 v[54:55], v[36:37], v[54:55] op_sel_hi:[0,1]
	v_pk_mul_f32 v[40:41], v[40:41], v[60:61]
	v_pk_mul_f32 v[42:43], v[42:43], v[62:63]
	v_pk_mul_f32 v[44:45], v[44:45], v[64:65]
	v_pk_mul_f32 v[46:47], v[46:47], v[66:67]
	v_pk_mul_f32 v[48:49], v[48:49], v[68:69]
	v_pk_mul_f32 v[50:51], v[50:51], v[70:71]
	v_pk_mul_f32 v[52:53], v[52:53], v[72:73]
	v_pk_mul_f32 v[54:55], v[54:55], v[74:75]
	global_store_dwordx4 v5, v[40:43], s[20:21]
	global_store_dwordx4 v5, v[44:47], s[20:21] offset:1024
	global_store_dwordx4 v5, v[48:51], s[20:21] offset:2048
	global_store_dwordx4 v5, v[52:55], s[20:21] offset:3072
	s_cmp_eq_u32 s25, 0
	s_cbranch_scc1 .Lfn_end
	s_mov_b64 s[18:19], s[26:27]
	s_add_u32 s20, s20, s23
	s_addc_u32 s21, s21, 0
	s_branch .Lfn_A_top
